# v33 + LRU-scan and S5-scan work items placed on the XCD owning their token rows
# baseline (speedup 1.0000x reference)
; __device__ __forceinline__ int launder(int v) { asm volatile("" : "+v"(v)); return v; }
; __device__ __forceinline__ void lru_scan1(const bf16_t* Ab, const bf16_t* Bb, const bf16_t* XC, const float* lam, float* PE, int bid, int G) {
;     const int gtid = bid * NTHR + launder(threadIdx.x), nthreads = G * NTHR;
;     for (int item = gtid; item < LRU_NC * D; item += nthreads) {
; __device__ __forceinline__ void lru_scan2(const bf16_t* Ab, const bf16_t* Bb, const bf16_t* XC, const float* lam, const float* PE, const bf16_t* gate, bf16_t* Y, int bid, int G) {
;     const int gtid = bid * NTHR + launder(threadIdx.x), nthreads = G * NTHR;
;     for (int item = gtid; item < LRU_NC * D; item += nthreads) {
.Lwpf_i:
	v_mov_b32_e32 v1, v246
	v_readlane_b32 s0, v254, 4
	s_cmp_lg_u32 s78, 0x100
	s_cbranch_scc1 .Llruperm_a
	s_lshr_b32 s100, s0, 9
	s_and_b32 s101, s100, 7
	s_lshl_b32 s101, s101, 5
	s_lshr_b32 s100, s100, 3
	s_or_b32 s100, s100, s101
	s_lshl_b32 s0, s100, 9
